# v13: sample memory cross-attention items split over two waves (128 keys each), partials merged through LDS
# speedup vs baseline: 1.0152x; 1.0027x over previous
; #define ATT_Q_RESET() do { __syncthreads(); if (tid == 0) *qctr = 0u; __syncthreads(); } while (0)
; #define ATT_Q_NEXT() __builtin_amdgcn_readfirstlane(lane == 0 ? (int)__hip_atomic_fetch_add(qctr, 1u, __ATOMIC_RELAXED, __HIP_MEMORY_SCOPE_WORKGROUP) : 0)
; __global__ void __launch_bounds__(512, 2) fwd_kernel(Params P) {
;     ...
;         ATT_Q_RESET();
;         for (int it = ATT_Q_NEXT() * G + cu; it < 768; it = ATT_Q_NEXT() * G + cu) {
;             if (it < 512) { AttMemS t{PROJ, P.in[I_CMK], P.in[I_CMV], it >> 2, it & 3, DRY}; attn_item(t); }
;             else { const int r = it - 512; AttSwS t{PROJ, P.in[I_CK], P.in[I_CV], P.out + O_KWS, P.out + O_VWS, P.in[I_SINK], r >> 1, r & 1, DRY}; attn_item(t); }
.LBB0_845:
	s_or_b64 exec, exec, s[6:7]
	v_readfirstlane_b32 s72, v183
	s_lshr_b32 s72, s72, 6
	s_and_b32 s73, s72, 1
	s_lshr_b32 s75, s72, 1
	s_cmp_lt_u32 s72, 4
	s_cbranch_scc1 .Lsa_assign
	s_mov_b32 s75, 2
	s_mov_b32 s73, 0
.Lsa_assign:
	s_mul_i32 s6, s75, s56
	s_add_i32 s39, s6, s2
	s_cmp_gt_u32 s72, 4
	s_cbranch_scc1 .Lsa_sync
	s_cmpk_gt_i32 s39, 0x2ff
	s_cbranch_scc1 .Lsa_sync
	v_bfe_u32 v3, v183, 5, 1
	v_lshlrev_b32_e32 v4, 3, v183
	v_lshlrev_b32_e32 v2, 3, v3
	v_and_b32_e32 v119, 0xc0, v4
	v_lshrrev_b32_e32 v4, 2, v183
	s_add_u32 s28, s42, 0x8f00000
	v_and_b32_e32 v4, 8, v4
	v_lshlrev_b32_e32 v124, 1, v2
	v_mbcnt_lo_u32_b32 v2, -1, 0
	s_addc_u32 s29, s43, 0
	v_mov_b32_e32 v115, 0
	v_and_b32_e32 v116, 31, v183
	v_lshlrev_b32_e32 v114, 2, v4
	v_mbcnt_hi_u32_b32 v134, -1, v2
	s_add_u32 s30, s42, 0x9700000
	v_and_b32_e32 v5, 7, v183
	v_bfe_u32 v130, v183, 3, 2
	v_mul_i32_i24_e32 v6, -4, v3
	v_lshl_add_u64 v[120:121], s[18:19], 0, v[114:115]
	v_lshlrev_b32_e32 v114, 2, v116
	s_movk_i32 s8, 0x65
	v_and_b32_e32 v2, 64, v134
	s_addc_u32 s31, s43, 0
	v_or_b32_e32 v117, 0x8000, v5
	v_add_u32_e32 v131, 1, v130
	v_and_b32_e32 v1, 4, v1
	v_lshlrev_b32_e32 v118, 2, v3
	v_lshl_add_u64 v[122:123], s[26:27], 0, v[114:115]
	v_cmp_gt_u32_e64 s[6:7], 8, v116
	v_or_b32_e32 v132, 0x8000, v116
	v_add3_u32 v133, v6, v5, s8
	s_movk_i32 s33, 0x3200
	s_mov_b32 s9, 0
	s_movk_i32 s34, 0x80
	v_lshlrev_b32_e32 v114, 2, v4
	s_mov_b64 s[10:11], 0x1600
	s_movk_i32 s35, 0x1000
	s_movk_i32 s36, 0x4000
	s_movk_i32 s37, 0x5000
	s_add_i32 s38, 0, 0x20210
	v_xor_b32_e32 v135, 32, v134
	v_add_u32_e32 v136, 64, v2
	v_mov_b32_e32 v137, 0xff800000
	s_branch .LBB0_849

; #define ATT_Q_NEXT() __builtin_amdgcn_readfirstlane(lane == 0 ? (int)__hip_atomic_fetch_add(qctr, 1u, __ATOMIC_RELAXED, __HIP_MEMORY_SCOPE_WORKGROUP) : 0)
; __global__ void __launch_bounds__(512, 2) fwd_kernel(Params P) {
;     ...
;         for (int it = ATT_Q_NEXT() * G + cu; it < 768; it = ATT_Q_NEXT() * G + cu) {
.LBB0_851:
	s_branch .Lsa_sync

; DI bf16x8 ld8f_bf(const float* p) { const f32x4 a = *(const f32x4*)p, b = *(const f32x4*)(p + 4); return __builtin_bit_cast(bf16x8, pack8(a, b)); }
;     DI bf16x8 kfrag_t(int tl, int kk) const { const int lane = threadIdx.x & 63; return ld8f_bf(krow(ck, nk, 32 * tl + (lane & 31)) + 16 * kk + 8 * (lane >> 5)); }
; template <class T> DI void attn_item(const T& t) {
;     ...
;     for (int kk = 0; kk < D / 16; ++kk) qf[kk] = t.qfrag(r, 16 * kk + 8 * h);
;     const int cbeg = t.cbeg();
;     if (!T::VSPLIT) {
; #pragma unroll
;         for (int kk = 0; kk < D / 16; ++kk) kf[kk] = t.kfrag_t(t.tile(cbeg), kk);
;     }
;     float m = t.m_init(r), l = t.l_init();
;     f32x16 o[D / 32];
; #pragma unroll
;     for (int dd = 0; dd < D / 32; ++dd)
; #pragma unroll
;         for (int i = 0; i < 16; ++i) o[dd][i] = 0.f;
;     bf16x8 vf[2][D / 32];
; #pragma unroll 1
;     for (int c = cbeg; c < NCH; ++c) {
;     DI bf16x8 kfrag_t(int tl, int kk) const { const int lane = threadIdx.x & 63; return ld8f_bf(mk + ((size_t)(b * 256 + 32 * tl + (lane & 31)) * 4 + hd) * 128 + 16 * kk + 8 * (lane >> 5)); }
;     DI bf16x8 vfrag_t(int tl, int s2, int dd) const { const int lane = threadIdx.x & 63; const float* p = mv + ((size_t)(b * 256 + 32 * tl + 16 * s2 + 4 * (lane >> 5)) * 4 + hd) * 128 + 32 * dd + (lane & 31); f32x4 a, c;
; #pragma unroll
;         for (int j = 0; j < 4; ++j) { a[j] = p[(size_t)j * 512]; c[j] = p[(size_t)(8 + j) * 512]; }
.LBB0_857:
	s_ashr_i32 s26, s39, 2
	s_lshl_b32 s18, s26, 3
	s_and_b32 s27, s39, 3
	v_add_u32_e32 v4, s18, v117
	v_mov_b64_e32 v[2:3], s[48:49]
	v_mad_i64_i32 v[2:3], s[16:17], v4, s33, v[2:3]
	s_lshl_b32 s8, s27, 8
	v_lshl_add_u64 v[2:3], v[2:3], 0, s[8:9]
	v_mov_b32_e32 v125, v115
	v_lshl_add_u64 v[2:3], v[2:3], 0, v[124:125]
	v_lshl_add_u64 v[4:5], v[2:3], 0, s[10:11]
	v_add_co_u32_e32 v2, vcc, s35, v2
	v_mov_b32_e32 v50, v115
	s_nop 0
	v_addc_co_u32_e32 v3, vcc, 0, v3, vcc
	global_load_dwordx4 v[82:85], v[4:5], off offset:32
	global_load_dwordx4 v[86:89], v[4:5], off offset:64
	global_load_dwordx4 v[90:93], v[4:5], off offset:96
	global_load_dwordx4 v[94:97], v[4:5], off offset:128
	global_load_dwordx4 v[98:101], v[4:5], off offset:160
	global_load_dwordx4 v[102:105], v[4:5], off offset:192
	global_load_dwordx4 v[106:109], v[2:3], off offset:1536
	global_load_dwordx4 v[110:113], v[4:5], off offset:224
	v_cmp_lt_i32_e32 vcc, v135, v136
	v_mov_b32_e32 v51, v115
	s_lshl_b32 s17, s26, 8
	v_cndmask_b32_e32 v2, v134, v135, vcc
	s_lshl_b32 s8, s27, 9
	v_lshlrev_b32_e32 v138, 2, v2
	v_mov_b32_e32 v52, v115
	v_mov_b32_e32 v53, v115
	v_mov_b32_e32 v54, v115
	v_mov_b32_e32 v55, v115
	v_mov_b32_e32 v56, v115
	v_mov_b32_e32 v57, v115
	v_mov_b32_e32 v58, v115
	v_mov_b32_e32 v59, v115
	v_mov_b32_e32 v60, v115
	v_mov_b32_e32 v61, v115
	v_mov_b32_e32 v62, v115
	v_mov_b32_e32 v63, v115
	v_mov_b32_e32 v64, v115
	v_mov_b32_e32 v65, v115
	v_mov_b64_e32 v[34:35], v[50:51]
	v_mov_b64_e32 v[18:19], v[50:51]
	v_mov_b64_e32 v[2:3], v[50:51]
	s_lshl_b32 s19, s27, 7
	s_lshl_b32 s16, s73, 7
	s_add_i32 s74, s16, 0x80
	v_or_b32_e32 v125, s17, v116
	v_lshl_add_u64 v[126:127], v[120:121], 0, s[8:9]
	v_lshl_add_u64 v[128:129], v[122:123], 0, s[8:9]
	v_or_b32_e32 v139, s17, v1
	v_mov_b32_e32 v140, 0
	v_mov_b32_e32 v141, 0xff800000
	v_mov_b64_e32 v[36:37], v[52:53]
	v_mov_b64_e32 v[38:39], v[54:55]
	v_mov_b64_e32 v[40:41], v[56:57]
	v_mov_b64_e32 v[42:43], v[58:59]
	v_mov_b64_e32 v[44:45], v[60:61]
	v_mov_b64_e32 v[46:47], v[62:63]
	v_mov_b64_e32 v[48:49], v[64:65]
	v_mov_b64_e32 v[20:21], v[52:53]
	v_mov_b64_e32 v[22:23], v[54:55]
	v_mov_b64_e32 v[24:25], v[56:57]
	v_mov_b64_e32 v[26:27], v[58:59]
	v_mov_b64_e32 v[28:29], v[60:61]
	v_mov_b64_e32 v[30:31], v[62:63]
	v_mov_b64_e32 v[32:33], v[64:65]
	v_mov_b64_e32 v[4:5], v[52:53]
	v_mov_b64_e32 v[6:7], v[54:55]
	v_mov_b64_e32 v[8:9], v[56:57]
	v_mov_b64_e32 v[10:11], v[58:59]
	v_mov_b64_e32 v[12:13], v[60:61]
	v_mov_b64_e32 v[14:15], v[62:63]
	v_mov_b64_e32 v[16:17], v[64:65]
	s_branch .LBB0_859
.LBB0_858:
	v_sub_f32_e32 v66, v66, v141
	v_exp_f32_e32 v146, v66
	v_sub_f32_e32 v66, v67, v141
	v_exp_f32_e32 v147, v66
	v_sub_f32_e32 v66, v68, v141
	v_exp_f32_e32 v148, v66
	v_add_f32_e32 v66, 0, v146
	v_add_f32_e32 v66, v147, v66
	v_sub_f32_e32 v72, v72, v141
	v_add_f32_e32 v149, v148, v66
	v_sub_f32_e32 v66, v69, v141
	v_exp_f32_e32 v150, v66
	v_sub_f32_e32 v66, v70, v141
	v_exp_f32_e32 v151, v66
	v_sub_f32_e32 v66, v71, v141
	v_exp_f32_e32 v152, v66
	v_add_u32_e32 v66, s16, v139
	v_ashrrev_i32_e32 v67, 31, v66
	v_lshlrev_b64 v[68:69], 11, v[66:67]
	v_lshl_add_u64 v[68:69], v[128:129], 0, v[68:69]
	v_add_co_u32_e32 v70, vcc, s36, v68
	v_add_u32_e32 v66, 16, v66
	s_nop 0
	v_addc_co_u32_e32 v71, vcc, 0, v69, vcc
	v_add_co_u32_e32 v142, vcc, s37, v68
	v_ashrrev_i32_e32 v67, 31, v66
	s_nop 0
	v_addc_co_u32_e32 v143, vcc, 0, v69, vcc
	v_add_co_u32_e32 v144, vcc, s35, v68
	v_lshlrev_b64 v[66:67], 11, v[66:67]
	s_nop 0
	v_addc_co_u32_e32 v145, vcc, 0, v69, vcc
	global_load_dword v153, v[142:143], off offset:-4096
	global_load_dword v154, v[142:143], off
	global_load_dword v155, v[144:145], off offset:2048
	global_load_dword v156, v[144:145], off offset:128
	global_load_dword v157, v[144:145], off offset:2176
	global_load_dword v158, v[142:143], off offset:2048
	global_load_dword v159, v[142:143], off offset:128
	global_load_dword v160, v[142:143], off offset:2176
	global_load_dword v161, v[142:143], off offset:256
	global_load_dword v162, v[142:143], off offset:2304
	global_load_dword v163, v[68:69], off
	global_load_dword v164, v[68:69], off offset:2048
	global_load_dword v165, v[68:69], off offset:128
	global_load_dword v166, v[68:69], off offset:2176
	global_load_dword v167, v[68:69], off offset:256
	global_load_dword v168, v[68:69], off offset:2304
	global_load_dword v169, v[68:69], off offset:2432
	global_load_dword v170, v[68:69], off offset:384
	global_load_dword v171, v[70:71], off offset:2048
	global_load_dword v172, v[144:145], off
	global_load_dword v173, v[70:71], off offset:128
	global_load_dword v174, v[70:71], off offset:2176
	global_load_dword v175, v[70:71], off offset:256
	global_load_dword v176, v[70:71], off offset:2304
	global_load_dword v177, v[70:71], off offset:2432
	global_load_dword v178, v[70:71], off offset:384
	v_lshl_add_u64 v[66:67], v[128:129], 0, v[66:67]
	global_load_dword v179, v[144:145], off offset:256
	global_load_dword v180, v[144:145], off offset:2304
	global_load_dword v181, v[144:145], off offset:2432
	global_load_dword v184, v[66:67], off
	global_load_dword v185, v[144:145], off offset:384
	v_add_co_u32_e32 v68, vcc, s37, v66
	s_add_i32 s16, s16, 32
	s_nop 0
	v_addc_co_u32_e32 v69, vcc, 0, v67, vcc
	global_load_dword v186, v[142:143], off offset:2432
	global_load_dword v187, v[68:69], off offset:-4096
	global_load_dword v188, v[142:143], off offset:384
	global_load_dword v189, v[66:67], off offset:2048
	v_add_co_u32_e32 v70, vcc, s36, v66
	s_cmp_eq_u32 s16, s74
	s_nop 0
	v_addc_co_u32_e32 v71, vcc, 0, v67, vcc
	v_add_co_u32_e32 v142, vcc, s35, v66
	s_waitcnt vmcnt(27)
; DI float fexp2(float x) { return __builtin_amdgcn_exp2f(x); }
; DI u32x4 pack8(f32x4 a, f32x4 b) { u32x4 w; w.x = pk2(a[0], a[1]); w.y = pk2(a[2], a[3]); w.z = pk2(b[0], b[1]); w.w = pk2(b[2], b[3]); return w; }
; DI bf16x8 ld8f_bf(const float* p) { const f32x4 a = *(const f32x4*)p, b = *(const f32x4*)(p + 4); return __builtin_bit_cast(bf16x8, pack8(a, b)); }
; DI bf16x8 pack_step(const f32x16& x, int s) { u32x4 p; p.x = pk2(x[8 * s], x[8 * s + 1]); p.y = pk2(x[8 * s + 2], x[8 * s + 3]); p.z = pk2(x[8 * s + 4], x[8 * s + 5]); p.w = pk2(x[8 * s + 6], x[8 * s + 7]); return __builtin_bit_cast(bf16x8, p); }
; #define MFMA32(a, b, c) __builtin_amdgcn_mfma_f32_32x32x16_bf16((a), (b), (c), 0, 0, 0)
;     DI bf16x8 kfrag_t(int tl, int kk) const { const int lane = threadIdx.x & 63; return ld8f_bf(krow(ck, nk, 32 * tl + (lane & 31)) + 16 * kk + 8 * (lane >> 5)); }
; template <class T> DI void attn_item(const T& t) {
;     ...
;         float ps = 0.f;
; #pragma unroll
;         for (int i = 0; i < 16; ++i) { const float p = fexp2(s[i] - m); s[i] = p; ps += p; }
;         ps += __shfl_xor(ps, 32);
;         l += ps;
; #pragma unroll
;         for (int s2 = 0; s2 < 2; ++s2) { const bf16x8 pb = pack_step(s, s2);
;             if (T::VSPLIT) {
; #pragma unroll
;                 for (int dd = 0; dd < D / 32; ++dd) vf[s2][dd] = t.vfrag_t(tl, s2, dd);
;             }
; #pragma unroll
;             for (int dd = 0; dd < D / 32; ++dd) o[dd] = MFMA32(vf[s2][dd], pb, o[dd]); }
;     DI bf16x8 kfrag_t(int tl, int kk) const { const int lane = threadIdx.x & 63; return ld8f_bf(mk + ((size_t)(b * 256 + 32 * tl + (lane & 31)) * 4 + hd) * 128 + 16 * kk + 8 * (lane >> 5)); }
;     DI bf16x8 vfrag_t(int tl, int s2, int dd) const { const int lane = threadIdx.x & 63; const float* p = mv + ((size_t)(b * 256 + 32 * tl + 16 * s2 + 4 * (lane >> 5)) * 4 + hd) * 128 + 32 * dd + (lane & 31); f32x4 a, c;
; #pragma unroll
;         for (int j = 0; j < 4; ++j) { a[j] = p[(size_t)j * 512]; c[j] = p[(size_t)(8 + j) * 512]; }
;         return __builtin_bit_cast(bf16x8, pack8(a, c)); }
	v_cvt_pk_bf16_f32 v145, v159, v160
	v_addc_co_u32_e32 v143, vcc, 0, v67, vcc
	global_load_dword v190, v[70:71], off offset:2048
	global_load_dword v191, v[142:143], off
	global_load_dword v192, v[142:143], off offset:2048
	global_load_dword v193, v[68:69], off
	global_load_dword v194, v[68:69], off offset:2048
	global_load_dword v195, v[66:67], off offset:128
	global_load_dword v196, v[70:71], off offset:128
	global_load_dword v197, v[66:67], off offset:2176
	global_load_dword v198, v[70:71], off offset:2176
	global_load_dword v199, v[142:143], off offset:128
	global_load_dword v200, v[142:143], off offset:2176
	global_load_dword v201, v[68:69], off offset:128
	global_load_dword v202, v[68:69], off offset:2176
	global_load_dword v203, v[66:67], off offset:256
	global_load_dword v204, v[66:67], off offset:2304
	global_load_dword v205, v[70:71], off offset:256
	global_load_dword v206, v[70:71], off offset:2304
	global_load_dword v207, v[142:143], off offset:256
	global_load_dword v208, v[142:143], off offset:2304
	global_load_dword v209, v[68:69], off offset:256
	global_load_dword v210, v[68:69], off offset:2304
	global_load_dword v211, v[66:67], off offset:2432
	global_load_dword v212, v[66:67], off offset:384
	global_load_dword v213, v[70:71], off offset:2432
	global_load_dword v214, v[70:71], off offset:384
	global_load_dword v215, v[142:143], off offset:2432
	global_load_dword v216, v[142:143], off offset:384
	global_load_dword v217, v[68:69], off offset:2432
	global_load_dword v218, v[68:69], off offset:384
	v_exp_f32_e32 v69, v72
	v_sub_f32_e32 v67, v73, v141
	v_add_f32_e32 v66, v150, v149
	v_exp_f32_e32 v142, v67
	v_sub_f32_e32 v67, v74, v141
	v_add_f32_e32 v66, v151, v66
	v_exp_f32_e32 v149, v67
	v_sub_f32_e32 v67, v75, v141
	v_add_f32_e32 v66, v152, v66
	v_exp_f32_e32 v219, v67
	v_sub_f32_e32 v67, v76, v141
	v_add_f32_e32 v66, v69, v66
	v_exp_f32_e32 v220, v67
	s_waitcnt vmcnt(52)
	v_cvt_pk_bf16_f32 v70, v163, v164
	s_waitcnt vmcnt(44)
	v_cvt_pk_bf16_f32 v71, v172, v155
	v_cvt_pk_bf16_f32 v72, v153, v171
	v_cvt_pk_bf16_f32 v73, v154, v158
	v_add_f32_e32 v66, v142, v66
	v_add_f32_e32 v66, v149, v66
	v_add_f32_e32 v66, v219, v66
	v_add_f32_e32 v221, v220, v66
	v_cvt_pk_bf16_f32 v66, v146, v147
	v_cvt_pk_bf16_f32 v67, v148, v150
	v_cvt_pk_bf16_f32 v68, v151, v152
	v_cvt_pk_bf16_f32 v69, v69, v142
	v_cvt_pk_bf16_f32 v142, v165, v166
	v_cvt_pk_bf16_f32 v143, v156, v157
	v_mfma_f32_32x32x16_bf16 v[50:65], v[70:73], v[66:69], v[50:65]
	v_sub_f32_e32 v70, v77, v141
	v_exp_f32_e32 v146, v70
	v_cvt_pk_bf16_f32 v70, v167, v168
	s_waitcnt vmcnt(36)
	v_cvt_pk_bf16_f32 v71, v179, v180
	v_cvt_pk_bf16_f32 v72, v175, v176
	v_cvt_pk_bf16_f32 v73, v161, v162
	v_cvt_pk_bf16_f32 v144, v173, v174
	v_sub_f32_e32 v74, v78, v141
	v_exp_f32_e32 v78, v74
	v_sub_f32_e32 v74, v79, v141
	v_exp_f32_e32 v79, v74
	v_cvt_pk_bf16_f32 v74, v170, v169
	v_mfma_f32_32x32x16_bf16 v[18:33], v[70:73], v[66:69], v[18:33]
	s_waitcnt vmcnt(33)
	v_cvt_pk_bf16_f32 v75, v185, v181
	v_cvt_pk_bf16_f32 v76, v178, v177
	s_waitcnt vmcnt(30)
	v_cvt_pk_bf16_f32 v77, v188, v186
	v_sub_f32_e32 v70, v80, v141
	v_exp_f32_e32 v80, v70
	v_sub_f32_e32 v70, v81, v141
	v_exp_f32_e32 v81, v70
	v_mfma_f32_32x32x16_bf16 v[34:49], v[142:145], v[66:69], v[34:49]
	s_waitcnt vmcnt(29)
	v_cvt_pk_bf16_f32 v70, v184, v189
	s_waitcnt vmcnt(28)
	v_cvt_pk_bf16_f32 v72, v187, v190
	s_waitcnt vmcnt(26)
	v_cvt_pk_bf16_f32 v71, v191, v192
	s_waitcnt vmcnt(24)
	v_cvt_pk_bf16_f32 v73, v193, v194
	v_mfma_f32_32x32x16_bf16 v[2:17], v[74:77], v[66:69], v[2:17]
	v_cvt_pk_bf16_f32 v66, v149, v219
	s_waitcnt vmcnt(21)
	v_cvt_pk_bf16_f32 v74, v195, v197
	s_waitcnt vmcnt(20)
	v_cvt_pk_bf16_f32 v76, v196, v198
	v_cvt_pk_bf16_f32 v67, v220, v146
	s_waitcnt vmcnt(18)
	v_cvt_pk_bf16_f32 v75, v199, v200
	v_cvt_pk_bf16_f32 v68, v78, v79
	s_waitcnt vmcnt(16)
	v_cvt_pk_bf16_f32 v77, v201, v202
	v_cvt_pk_bf16_f32 v69, v80, v81
	s_nop 1
	v_mfma_f32_32x32x16_bf16 v[50:65], v[70:73], v[66:69], v[50:65]
	v_add_f32_e32 v70, v146, v221
	v_add_f32_e32 v70, v78, v70
	v_add_f32_e32 v78, v79, v70
	s_waitcnt vmcnt(14)
	v_cvt_pk_bf16_f32 v70, v203, v204
	s_waitcnt vmcnt(10)
	v_cvt_pk_bf16_f32 v71, v207, v208
	v_cvt_pk_bf16_f32 v72, v205, v206
	s_waitcnt vmcnt(8)
	v_cvt_pk_bf16_f32 v73, v209, v210
	v_mfma_f32_32x32x16_bf16 v[34:49], v[74:77], v[66:69], v[34:49]
	v_add_f32_e32 v74, v80, v78
	v_add_f32_e32 v78, v81, v74
	s_waitcnt vmcnt(6)
	v_cvt_pk_bf16_f32 v74, v212, v211
	s_waitcnt vmcnt(2)
	v_cvt_pk_bf16_f32 v75, v216, v215
	v_cvt_pk_bf16_f32 v76, v214, v213
	s_waitcnt vmcnt(0)
	v_cvt_pk_bf16_f32 v77, v218, v217
	ds_bpermute_b32 v79, v138, v78
	v_mfma_f32_32x32x16_bf16 v[18:33], v[70:73], v[66:69], v[18:33]
	s_waitcnt lgkmcnt(0)
	v_add_f32_e32 v70, v78, v79
	v_add_f32_e32 v140, v140, v70
	v_mfma_f32_32x32x16_bf16 v[2:17], v[74:77], v[66:69], v[2:17]
	s_cbranch_scc1 .LBB0_861

; DI float fexp2(float x) { return __builtin_amdgcn_exp2f(x); }
; DI float frcp(float x) { return __builtin_amdgcn_rcpf(x); }
; DI bf16x8 pack_step(const f32x16& x, int s) { u32x4 p; p.x = pk2(x[8 * s], x[8 * s + 1]); p.y = pk2(x[8 * s + 2], x[8 * s + 3]); p.z = pk2(x[8 * s + 4], x[8 * s + 5]); p.w = pk2(x[8 * s + 6], x[8 * s + 7]); return __builtin_bit_cast(bf16x8, p); }
; #define MFMA32(a, b, c) __builtin_amdgcn_mfma_f32_32x32x16_bf16((a), (b), (c), 0, 0, 0)
; template <class T> DI void attn_item(const T& t) {
;     ...
;         if (__builtin_amdgcn_ballot_w64(need) != 0ull) {
;             const float mn = need ? mx : m;
;             const float sc = fexp2(m - mn);
;             l *= sc; m = mn;
; #pragma unroll
;             for (int dd = 0; dd < D / 32; ++dd)
; #pragma unroll
;                 for (int i = 0; i < 16; ++i) o[dd][i] *= sc;
;         }
;         float ps = 0.f;
; #pragma unroll
;         for (int i = 0; i < 16; ++i) { const float p = fexp2(s[i] - m); s[i] = p; ps += p; }
;         ps += __shfl_xor(ps, 32);
;         l += ps;
; #pragma unroll
;         for (int s2 = 0; s2 < 2; ++s2) { const bf16x8 pb = pack_step(s, s2);
;             if (T::VSPLIT) {
; #pragma unroll
;                 for (int dd = 0; dd < D / 32; ++dd) vf[s2][dd] = t.vfrag_t(tl, s2, dd);
;             }
; #pragma unroll
;             for (int dd = 0; dd < D / 32; ++dd) o[dd] = MFMA32(vf[s2][dd], pb, o[dd]); }
;     }
;     const float inv = frcp(l);
.LBB0_861:
	s_nop 15
	s_nop 15
	s_cmp_eq_u32 s73, 0
	s_cbranch_scc1 .Lsa_sync
	s_mul_i32 s76, s75, 0x4400
	v_lshlrev_b32_e32 v215, 4, v182
	v_lshlrev_b32_e32 v216, 3, v182
	v_add_u32_e32 v215, s76, v215
	v_add_u32_e32 v216, s76, v216
	v_add_u32_e32 v216, 0x4000, v216
	ds_write_b128 v215, v[50:53] offset:12288
	ds_write_b128 v215, v[54:57] offset:13312
	ds_write_b128 v215, v[58:61] offset:14336
	ds_write_b128 v215, v[62:65] offset:15360
	ds_write_b128 v215, v[34:37] offset:8192
	ds_write_b128 v215, v[38:41] offset:9216
	ds_write_b128 v215, v[42:45] offset:10240
	ds_write_b128 v215, v[46:49] offset:11264
	ds_write_b128 v215, v[18:21] offset:4096
	ds_write_b128 v215, v[22:25] offset:5120
	ds_write_b128 v215, v[26:29] offset:6144
	ds_write_b128 v215, v[30:33] offset:7168
	ds_write_b128 v215, v[2:5]
	ds_write_b128 v215, v[6:9] offset:1024
	ds_write_b128 v215, v[10:13] offset:2048
	ds_write_b128 v215, v[14:17] offset:3072
	ds_write_b64 v216, v[140:141]
.Lsa_sync:
	s_waitcnt vmcnt(0) lgkmcnt(0)
	s_barrier
	s_cmp_gt_u32 s72, 3
	s_cbranch_scc1 .LBB0_866
	s_cmp_eq_u32 s73, 1
	s_cbranch_scc1 .LBB0_866
	s_cmpk_gt_i32 s39, 0x2ff
	s_cbranch_scc1 .LBB0_866
	s_mul_i32 s76, s75, 0x4400
	v_lshlrev_b32_e32 v215, 4, v182
	v_lshlrev_b32_e32 v216, 3, v182
	v_add_u32_e32 v215, s76, v215
	v_add_u32_e32 v216, s76, v216
	v_add_u32_e32 v216, 0x4000, v216
	ds_read_b64 v[208:209], v216
	s_waitcnt lgkmcnt(0)
	ds_read_b128 v[142:145], v215
	ds_read_b128 v[146:149], v215 offset:1024
	ds_read_b128 v[150:153], v215 offset:2048
	ds_read_b128 v[154:157], v215 offset:3072
	ds_read_b128 v[158:161], v215 offset:4096
	ds_read_b128 v[162:165], v215 offset:5120
	ds_read_b128 v[166:169], v215 offset:6144
	ds_read_b128 v[170:173], v215 offset:7168
	ds_read_b128 v[174:177], v215 offset:8192
	ds_read_b128 v[178:181], v215 offset:9216
	ds_read_b128 v[184:187], v215 offset:10240
	ds_read_b128 v[188:191], v215 offset:11264
	ds_read_b128 v[192:195], v215 offset:12288
	ds_read_b128 v[196:199], v215 offset:13312
	ds_read_b128 v[200:203], v215 offset:14336
	ds_read_b128 v[204:207], v215 offset:15360
	v_max_f32_e32 v214, v141, v209
	v_sub_f32_e32 v210, v141, v214
	v_sub_f32_e32 v212, v209, v214
	v_exp_f32_e32 v210, v210
	v_exp_f32_e32 v212, v212
	v_mov_b32_e32 v141, v214
	s_nop 0
	v_mul_f32_e32 v140, v140, v210
	v_fmac_f32_e32 v140, v208, v212
	s_waitcnt lgkmcnt(15)
	v_pk_mul_f32 v[2:3], v[2:3], v[210:211] op_sel_hi:[1,0]
	v_pk_fma_f32 v[2:3], v[142:143], v[212:213], v[2:3] op_sel_hi:[1,0,1]
	v_pk_mul_f32 v[4:5], v[4:5], v[210:211] op_sel_hi:[1,0]
	v_pk_fma_f32 v[4:5], v[144:145], v[212:213], v[4:5] op_sel_hi:[1,0,1]
	s_waitcnt lgkmcnt(14)
	v_pk_mul_f32 v[6:7], v[6:7], v[210:211] op_sel_hi:[1,0]
	v_pk_fma_f32 v[6:7], v[146:147], v[212:213], v[6:7] op_sel_hi:[1,0,1]
	v_pk_mul_f32 v[8:9], v[8:9], v[210:211] op_sel_hi:[1,0]
	v_pk_fma_f32 v[8:9], v[148:149], v[212:213], v[8:9] op_sel_hi:[1,0,1]
	s_waitcnt lgkmcnt(13)
	v_pk_mul_f32 v[10:11], v[10:11], v[210:211] op_sel_hi:[1,0]
	v_pk_fma_f32 v[10:11], v[150:151], v[212:213], v[10:11] op_sel_hi:[1,0,1]
	v_pk_mul_f32 v[12:13], v[12:13], v[210:211] op_sel_hi:[1,0]
	v_pk_fma_f32 v[12:13], v[152:153], v[212:213], v[12:13] op_sel_hi:[1,0,1]
	s_waitcnt lgkmcnt(12)
	v_pk_mul_f32 v[14:15], v[14:15], v[210:211] op_sel_hi:[1,0]
	v_pk_fma_f32 v[14:15], v[154:155], v[212:213], v[14:15] op_sel_hi:[1,0,1]
	v_pk_mul_f32 v[16:17], v[16:17], v[210:211] op_sel_hi:[1,0]
	v_pk_fma_f32 v[16:17], v[156:157], v[212:213], v[16:17] op_sel_hi:[1,0,1]
	s_waitcnt lgkmcnt(11)
	v_pk_mul_f32 v[18:19], v[18:19], v[210:211] op_sel_hi:[1,0]
	v_pk_fma_f32 v[18:19], v[158:159], v[212:213], v[18:19] op_sel_hi:[1,0,1]
	v_pk_mul_f32 v[20:21], v[20:21], v[210:211] op_sel_hi:[1,0]
	v_pk_fma_f32 v[20:21], v[160:161], v[212:213], v[20:21] op_sel_hi:[1,0,1]
	s_waitcnt lgkmcnt(10)
	v_pk_mul_f32 v[22:23], v[22:23], v[210:211] op_sel_hi:[1,0]
	v_pk_fma_f32 v[22:23], v[162:163], v[212:213], v[22:23] op_sel_hi:[1,0,1]
	v_pk_mul_f32 v[24:25], v[24:25], v[210:211] op_sel_hi:[1,0]
	v_pk_fma_f32 v[24:25], v[164:165], v[212:213], v[24:25] op_sel_hi:[1,0,1]
	s_waitcnt lgkmcnt(9)
	v_pk_mul_f32 v[26:27], v[26:27], v[210:211] op_sel_hi:[1,0]
	v_pk_fma_f32 v[26:27], v[166:167], v[212:213], v[26:27] op_sel_hi:[1,0,1]
	v_pk_mul_f32 v[28:29], v[28:29], v[210:211] op_sel_hi:[1,0]
	v_pk_fma_f32 v[28:29], v[168:169], v[212:213], v[28:29] op_sel_hi:[1,0,1]
	s_waitcnt lgkmcnt(8)
	v_pk_mul_f32 v[30:31], v[30:31], v[210:211] op_sel_hi:[1,0]
	v_pk_fma_f32 v[30:31], v[170:171], v[212:213], v[30:31] op_sel_hi:[1,0,1]
	v_pk_mul_f32 v[32:33], v[32:33], v[210:211] op_sel_hi:[1,0]
	v_pk_fma_f32 v[32:33], v[172:173], v[212:213], v[32:33] op_sel_hi:[1,0,1]
	s_waitcnt lgkmcnt(7)
	v_pk_mul_f32 v[34:35], v[34:35], v[210:211] op_sel_hi:[1,0]
	v_pk_fma_f32 v[34:35], v[174:175], v[212:213], v[34:35] op_sel_hi:[1,0,1]
	v_pk_mul_f32 v[36:37], v[36:37], v[210:211] op_sel_hi:[1,0]
	v_pk_fma_f32 v[36:37], v[176:177], v[212:213], v[36:37] op_sel_hi:[1,0,1]
	s_waitcnt lgkmcnt(6)
	v_pk_mul_f32 v[38:39], v[38:39], v[210:211] op_sel_hi:[1,0]
	v_pk_fma_f32 v[38:39], v[178:179], v[212:213], v[38:39] op_sel_hi:[1,0,1]
	v_pk_mul_f32 v[40:41], v[40:41], v[210:211] op_sel_hi:[1,0]
	v_pk_fma_f32 v[40:41], v[180:181], v[212:213], v[40:41] op_sel_hi:[1,0,1]
	s_waitcnt lgkmcnt(5)
	v_pk_mul_f32 v[42:43], v[42:43], v[210:211] op_sel_hi:[1,0]
	v_pk_fma_f32 v[42:43], v[184:185], v[212:213], v[42:43] op_sel_hi:[1,0,1]
	v_pk_mul_f32 v[44:45], v[44:45], v[210:211] op_sel_hi:[1,0]
	v_pk_fma_f32 v[44:45], v[186:187], v[212:213], v[44:45] op_sel_hi:[1,0,1]
	s_waitcnt lgkmcnt(4)
	v_pk_mul_f32 v[46:47], v[46:47], v[210:211] op_sel_hi:[1,0]
	v_pk_fma_f32 v[46:47], v[188:189], v[212:213], v[46:47] op_sel_hi:[1,0,1]
	v_pk_mul_f32 v[48:49], v[48:49], v[210:211] op_sel_hi:[1,0]
	v_pk_fma_f32 v[48:49], v[190:191], v[212:213], v[48:49] op_sel_hi:[1,0,1]
	s_waitcnt lgkmcnt(3)
	v_pk_mul_f32 v[50:51], v[50:51], v[210:211] op_sel_hi:[1,0]
	v_pk_fma_f32 v[50:51], v[192:193], v[212:213], v[50:51] op_sel_hi:[1,0,1]
	v_pk_mul_f32 v[52:53], v[52:53], v[210:211] op_sel_hi:[1,0]
	v_pk_fma_f32 v[52:53], v[194:195], v[212:213], v[52:53] op_sel_hi:[1,0,1]
	s_waitcnt lgkmcnt(2)
	v_pk_mul_f32 v[54:55], v[54:55], v[210:211] op_sel_hi:[1,0]
	v_pk_fma_f32 v[54:55], v[196:197], v[212:213], v[54:55] op_sel_hi:[1,0,1]
	v_pk_mul_f32 v[56:57], v[56:57], v[210:211] op_sel_hi:[1,0]
	v_pk_fma_f32 v[56:57], v[198:199], v[212:213], v[56:57] op_sel_hi:[1,0,1]
	s_waitcnt lgkmcnt(1)
	v_pk_mul_f32 v[58:59], v[58:59], v[210:211] op_sel_hi:[1,0]
	v_pk_fma_f32 v[58:59], v[200:201], v[212:213], v[58:59] op_sel_hi:[1,0,1]
	v_pk_mul_f32 v[60:61], v[60:61], v[210:211] op_sel_hi:[1,0]
	v_pk_fma_f32 v[60:61], v[202:203], v[212:213], v[60:61] op_sel_hi:[1,0,1]
	s_waitcnt lgkmcnt(0)
	v_pk_mul_f32 v[62:63], v[62:63], v[210:211] op_sel_hi:[1,0]
	v_pk_fma_f32 v[62:63], v[204:205], v[212:213], v[62:63] op_sel_hi:[1,0,1]
	v_pk_mul_f32 v[64:65], v[64:65], v[210:211] op_sel_hi:[1,0]
	v_pk_fma_f32 v[64:65], v[206:207], v[212:213], v[64:65] op_sel_hi:[1,0,1]

; #define ATT_Q_NEXT() __builtin_amdgcn_readfirstlane(lane == 0 ? (int)__hip_atomic_fetch_add(qctr, 1u, __ATOMIC_RELAXED, __HIP_MEMORY_SCOPE_WORKGROUP) : 0)
; __global__ void __launch_bounds__(512, 2) fwd_kernel(Params P) {
;     ...
;         for (int it = ATT_Q_NEXT() * G + cu; it < 768; it = ATT_Q_NEXT() * G + cu) {
;             if (it < 512) { AttMemS t{PROJ, P.in[I_CMK], P.in[I_CMV], it >> 2, it & 3, DRY}; attn_item(t); }
;             else { const int r = it - 512; AttSwS t{PROJ, P.in[I_CK], P.in[I_CV], P.out + O_KWS, P.out + O_VWS, P.in[I_SINK], r >> 1, r & 1, DRY}; attn_item(t); }
;         }
.LBB0_863:
	s_or_b64 exec, exec, s[16:17]
	s_branch .LBB0_866
